# MLA loop: K/V tiles double-buffered in LDS (one barrier per key tile, LDS refill overlapped with the tile's compute)
# baseline (speedup 1.0000x reference)
; DI int TID() { int t = (int)__builtin_amdgcn_workitem_id_x(); asm volatile("" : "+v"(t)); return t; }
; template <int DQK, int DV, bool BAND> ...
;     ...
;   const int tid = TID(), lane = tid & 63, w = tid >> 6, r32 = lane & 31, hi = lane >> 5;
;   u16* Ks = (u16*)smem; u16* Vs = (u16*)(smem + 17408); float* sc = (float*)(smem + 34816) + w * 64;
;   const int qw0 = q0 + w * 32, qi = qw0 + r32;
;   bf16x8 qf[ND0];
; #pragma unroll
;   for (int d0 = 0; d0 < ND0; ++d0) qf[d0] = *(const bf16x8*)(Q + (size_t)(w * 32 + r32) * ldq + d0 * 16 + hi * 8);
;   f32x16 o[NCB];
; #pragma unroll
;   for (int cb = 0; cb < NCB; ++cb)
; #pragma unroll
;     for (int r = 0; r < 16; ++r) o[cb][r] = 0.f;
;   float m_run = -INFINITY, l_run = 0.f;
;   int kt_lo = 0, kt_hi = nkeys >> 6;
;   if (BAND) { kt_lo = max(0, (q0 >> 6) - 1); kt_hi = min(nkeys >> 6, (q0 >> 6) + 3); }
;   u32x4 kreg[KCH], vreg[VCH];
;     ...
;   constexpr bool PREF = true;
;   if (PREF) ALOAD(kt_lo);
; DI void item_attn(const Params& p, int l, const Chunk& ck, int it, char* smem) {
;   const int S = ck.S;
;   if (it < 8 * MTN) {
;     static_assert(8 * MTN == 1024, "MLA item swizzle assumes 1024 items");
;     const int rnd = it >> 9, x = it & 7, jj = (it & 511) >> 3; const int qs = ck.sshift - 7, ppx = 64 >> qs;
;     const int bh = rnd * (8 * ppx) + x * ppx + (jj >> qs), qblk = jj & ((1 << qs) - 1);
;     const int h = bh & 7, bl = bh >> 3; const int t0 = qblk * 128, lt0 = bl * S + t0;
;     const u16* Q = (const u16*)(p.ws + OFF_QM) + (size_t)lt0 * 768 + h * 96;
;     const u16* K = (const u16*)(p.ws + OFF_KM) + (size_t)(bl * S) * 768 + h * 96;
;     const u16* Vt = (const u16*)(p.ws + OFF_VMT) + ((size_t)(bl * 8 + h) * 64) * S;
;     u16* O = (u16*)(p.ws + OFF_BR) + (size_t)(1 * CT + lt0) * 512 + h * 64;
;     (void)t0;
;     attn_block<96, 64, false>(Q, 768, K, 768, Vt, S, S, t0, 0.f, O, 512, nullptr, 0, smem);
.LBB1_317:
	s_ashr_i32 s21, s55, 6
	s_and_b32 s0, s55, 7
	s_and_b32 s29, s21, -8
	s_bfe_u32 s20, s55, 0x60003
	s_or_b32 s0, s29, s0
	s_lshr_b32 s30, s20, s35
	s_mul_i32 s0, s0, s42
	s_add_i32 s21, s0, s30
	s_and_b32 s20, s20, s43
	s_ashr_i32 s22, s21, 3
	s_lshl_b32 s20, s20, 7
	s_mul_i32 s26, s22, s2
	s_add_i32 s20, s26, s20
	s_and_b32 s28, s16, 7
	s_and_b32 s0, s21, 7
	s_mul_i32 s23, s20, 0x600
	s_mul_hi_i32 s22, s20, 0x600
	s_add_u32 s23, s93, s23
	s_addc_u32 s24, s94, s22
	s_mul_i32 s27, s0, 0xc0
	s_add_u32 s22, s23, s27
	v_mov_b32_e32 v2, v172
	s_addc_u32 s23, s24, 0
	s_mul_hi_i32 s25, s74, s21
	s_mul_i32 s24, s74, s21
	s_movk_i32 s21, 0xffe0
	v_ashrrev_i32_e32 v0, 1, v2
	v_bfe_u32 v3, v2, 5, 1
	s_waitcnt vmcnt(9)
	v_and_b32_e32 v122, 0xffffffe0, v0
	v_bfi_b32 v0, s21, v0, v2
	v_mov_b64_e32 v[4:5], s[22:23]
	s_movk_i32 s31, 0x600
	v_mad_i64_i32 v[4:5], s[22:23], v0, s31, v[4:5]
	v_lshlrev_b32_e32 v0, 4, v3
	v_lshl_add_u64 v[4:5], v[4:5], 0, v[0:1]
	global_load_dwordx4 v[66:69], v[4:5], off
	global_load_dwordx4 v[70:73], v[4:5], off offset:32
	global_load_dwordx4 v[74:77], v[4:5], off offset:64
	global_load_dwordx4 v[78:81], v[4:5], off offset:96
	global_load_dwordx4 v[82:85], v[4:5], off offset:128
	global_load_dwordx4 v[86:89], v[4:5], off offset:160
	v_lshlrev_b32_e32 v4, 2, v2
	s_mov_b32 s21, 0x2aaaaaab
	v_and_b32_e32 v29, 0xffffff00, v4
	v_mul_hi_i32 v4, v2, s21
	v_lshrrev_b32_e32 v5, 31, v4
	v_ashrrev_i32_e32 v4, 1, v4
	v_add_u32_e32 v30, v4, v5
	v_add_u32_e32 v4, 0x100, v2
	v_mul_hi_i32 v5, v4, s21
	v_lshrrev_b32_e32 v6, 31, v5
	v_ashrrev_i32_e32 v5, 1, v5
	v_add_u32_e32 v31, v5, v6
	v_add_u32_e32 v6, 0x200, v2
	s_lshl_b64 s[24:25], s[24:25], 1
	v_mul_hi_i32 v5, v6, s21
	v_ashrrev_i32_e32 v12, 3, v2
	s_waitcnt lgkmcnt(0)
	v_ashrrev_i32_e32 v16, 3, v4
	s_add_u32 s24, s17, s24
	v_lshrrev_b32_e32 v7, 31, v5
	v_ashrrev_i32_e32 v5, 1, v5
	v_mad_i64_i32 v[14:15], s[22:23], v12, s2, 0
	v_mad_i64_i32 v[18:19], s[22:23], v16, s2, 0
	s_addc_u32 s25, s34, s25
	v_add_u32_e32 v36, v5, v7
	v_lshlrev_b32_e32 v5, 4, v2
	s_mul_i32 s22, s26, 0x600
	v_and_b32_e32 v8, 0x70, v5
	v_mov_b32_e32 v9, v1
	s_mul_hi_i32 s23, s26, 0x600
	s_add_u32 s21, s79, s22
	v_lshl_add_u64 v[10:11], s[24:25], 0, v[8:9]
	s_addc_u32 s25, s92, s23
	s_add_u32 s24, s21, s27
	v_mad_u64_u32 v[6:7], s[26:27], v36, -12, v[6:7]
	s_addc_u32 s25, s25, 0
	v_lshlrev_b32_e32 v20, 3, v6
	v_mad_u64_u32 v[4:5], s[26:27], v31, -12, v[4:5]
	v_lshl_add_u64 v[18:19], v[18:19], 1, v[10:11]
	v_lshl_add_u64 v[10:11], v[14:15], 1, v[10:11]
	v_ashrrev_i32_e32 v21, 31, v20
	v_lshlrev_b32_e32 v22, 3, v4
	v_mad_u64_u32 v[24:25], s[26:27], v30, -12, v[2:3]
	global_load_dwordx4 v[94:97], v[18:19], off
	global_load_dwordx4 v[90:93], v[10:11], off
	v_mov_b64_e32 v[10:11], s[24:25]
	v_ashrrev_i32_e32 v23, 31, v22
	v_lshlrev_b32_e32 v26, 3, v24
	v_mad_i64_i32 v[14:15], s[24:25], v36, s31, v[10:11]
	v_lshlrev_b64 v[18:19], 1, v[20:21]
	v_ashrrev_i32_e32 v27, 31, v26
	v_lshl_add_u64 v[14:15], v[14:15], 0, v[18:19]
	v_mad_i64_i32 v[20:21], s[24:25], v31, s31, v[10:11]
	v_lshlrev_b64 v[22:23], 1, v[22:23]
	v_lshl_add_u64 v[20:21], v[20:21], 0, v[22:23]
	global_load_dwordx4 v[102:105], v[14:15], off
	global_load_dwordx4 v[98:101], v[20:21], off
	v_mad_i64_i32 v[10:11], s[24:25], v30, s31, v[10:11]
	v_lshlrev_b64 v[14:15], 1, v[26:27]
	v_lshl_add_u64 v[10:11], v[10:11], 0, v[14:15]
	global_load_dwordx4 v[106:109], v[10:11], off
	s_movk_i32 s24, 0xd0
	s_movk_i32 s26, 0x88
	v_mul_lo_u32 v38, v30, s24
	v_mul_lo_u32 v40, v31, s24
	v_mul_lo_u32 v42, v36, s24
	v_mad_u64_u32 v[32:33], s[24:25], v12, s26, v[8:9]
	v_mad_u64_u32 v[34:35], s[24:25], v16, s26, v[8:9]
	s_or_b32 s24, s29, s28
	s_mul_i32 s24, s42, s24
	s_add_i32 s24, s30, s24
	s_ashr_i32 s25, s24, 31
	v_and_b32_e32 v121, 31, v2
	v_ashrrev_i32_e32 v13, 31, v12
	v_or_b32_e32 v120, v29, v0
	s_lshl_b64 s[24:25], s[24:25], 7
	v_and_b32_e32 v0, 7, v2
	v_lshlrev_b32_e32 v28, 3, v3
	v_cmp_eq_u32_e64 s[36:37], 0, v3
	v_lshlrev_b32_e32 v123, 2, v3
	v_mul_u32_u24_e32 v3, 0x44, v121
	v_lshlrev_b32_e32 v39, 4, v4
	v_lshl_add_u64 v[4:5], v[12:13], 1, s[24:25]
	v_lshlrev_b32_e32 v0, 4, v0
	v_lshl_add_u32 v125, v3, 1, v28
	v_mad_u64_u32 v[2:3], s[26:27], s2, v4, v[0:1]
	v_ashrrev_i32_e32 v17, 31, v16
	v_mad_i32_i24 v3, s2, v5, v3
	s_mov_b64 s[26:27], 0x15080080
	v_lshl_add_u64 v[110:111], v[2:3], 0, s[26:27]
	v_lshl_add_u64 v[2:3], v[16:17], 1, s[24:25]
	v_mad_u64_u32 v[4:5], s[24:25], s2, v2, v[0:1]
	v_mad_i32_i24 v5, s2, v3, v5
	v_mov_b64_e32 v[2:3], s[22:23]
	v_lshl_add_u64 v[112:113], v[4:5], 0, s[26:27]
	v_mad_i64_i32 v[4:5], s[22:23], v36, s31, v[2:3]
	s_mov_b64 s[26:27], 0x13898000
	s_add_i32 s22, s54, s30
	v_lshl_add_u64 v[4:5], v[4:5], 0, s[26:27]
	s_and_b32 s24, s22, 7
	v_mad_u64_u32 v[4:5], s[22:23], s24, v203, v[4:5]
	s_waitcnt vmcnt(19)
; template <int DQK, int DV, bool BAND> ...
;     ...
;   f32x16 o[NCB];
; #pragma unroll
;   for (int cb = 0; cb < NCB; ++cb)
; #pragma unroll
;     for (int r = 0; r < 16; ++r) o[cb][r] = 0.f;
;   float m_run = -INFINITY, l_run = 0.f;
;   int kt_lo = 0, kt_hi = nkeys >> 6;
;   if (BAND) { kt_lo = max(0, (q0 >> 6) - 1); kt_hi = min(nkeys >> 6, (q0 >> 6) + 3); }
;   u32x4 kreg[KCH], vreg[VCH];
;     ...
;   constexpr bool PREF = true;
;   if (PREF) ALOAD(kt_lo);
;   for (int kt = kt_lo; kt < kt_hi; ++kt) {
;     __syncthreads();
;     if (!PREF) ALOAD(kt);
; #pragma unroll
;     for (int i = 0; i < KCH; ++i) { const int cid = tid + 256 * i, row = cid / KCPR, c8 = cid - row * KCPR; *(u32x4*)&Ks[row * KLD + c8 * 8] = kreg[i]; }
; #pragma unroll
;     for (int i = 0; i < VCH; ++i) { const int cid = tid + 256 * i, row = cid >> 3, c8 = cid & 7;
;       *(u32x2*)&Vs[row * VLD + c8 * 8] = u32x2{vreg[i][0], vreg[i][1]}; *(u32x2*)&Vs[row * VLD + c8 * 8 + 4] = u32x2{vreg[i][2], vreg[i][3]}; }
;     __syncthreads();
;     if (PREF && kt + 1 < kt_hi) ALOAD(kt + 1);
	v_lshl_add_u64 v[114:115], v[4:5], 0, v[18:19]
	v_mad_i64_i32 v[4:5], s[22:23], v31, s31, v[2:3]
	v_mad_i64_i32 v[2:3], s[22:23], v30, s31, v[2:3]
	v_lshl_add_u64 v[4:5], v[4:5], 0, s[26:27]
	v_lshl_add_u64 v[2:3], v[2:3], 0, s[26:27]
	v_mad_u64_u32 v[4:5], s[22:23], s24, v203, v[4:5]
	v_mad_u64_u32 v[2:3], s[22:23], s24, v203, v[2:3]
	v_lshl_or_b32 v124, v121, 2, v29
	v_lshlrev_b32_e32 v37, 4, v24
	v_lshlrev_b32_e32 v41, 4, v6
	v_add_u32_e32 v33, v28, v28
	v_mul_u32_u24_e32 v35, 0xd0, v121
	v_lshl_add_u64 v[116:117], v[4:5], 0, v[22:23]
	v_lshl_add_u64 v[118:119], v[2:3], 0, v[14:15]
	v_mov_b32_e32 v2, v1
	v_mov_b32_e32 v3, v1
	v_mov_b32_e32 v4, v1
	v_mov_b32_e32 v5, v1
	v_mov_b32_e32 v6, v1
	v_mov_b32_e32 v7, v1
	v_mov_b32_e32 v8, v1
	v_mov_b32_e32 v10, v1
	v_mov_b32_e32 v11, v1
	v_mov_b32_e32 v12, v1
	v_mov_b32_e32 v13, v1
	v_mov_b32_e32 v14, v1
	v_mov_b32_e32 v15, v1
	v_mov_b32_e32 v16, v1
	v_mov_b32_e32 v17, v1
	v_mov_b32_e32 v18, v1
	v_mov_b32_e32 v19, v1
	v_mov_b32_e32 v20, v1
	v_mov_b32_e32 v21, v1
	v_mov_b32_e32 v22, v1
	v_mov_b32_e32 v23, v1
	v_mov_b32_e32 v24, v1
	v_mov_b32_e32 v25, v1
	v_mov_b32_e32 v26, v1
	v_mov_b32_e32 v27, v1
	v_mov_b32_e32 v28, v1
	v_mov_b32_e32 v29, v1
	v_mov_b32_e32 v30, v1
	v_mov_b32_e32 v31, v1
	v_mov_b32_e32 v0, v1
	v_add_u32_e32 v130, 0x4400, v32
	v_add_u32_e32 v132, v33, v35
	v_mov_b64_e32 v[32:33], v[30:31]
	s_mov_b32 s21, 0
	s_waitcnt vmcnt(18)
	v_mov_b32_e32 v126, 0
	v_mov_b32_e32 v133, 0xff800000
	v_add_u32_e32 v127, v37, v38
	v_add_u32_e32 v128, v39, v40
	v_add_u32_e32 v129, v41, v42
	v_add_u32_e32 v131, 0x4400, v34
	v_mov_b64_e32 v[30:31], v[28:29]
	v_mov_b64_e32 v[28:29], v[26:27]
	v_mov_b64_e32 v[26:27], v[24:25]
	v_mov_b64_e32 v[24:25], v[22:23]
	v_mov_b64_e32 v[22:23], v[20:21]
	v_mov_b64_e32 v[20:21], v[18:19]
	v_mov_b64_e32 v[18:19], v[16:17]
	v_mov_b64_e32 v[16:17], v[14:15]
	v_mov_b64_e32 v[14:15], v[12:13]
	v_mov_b64_e32 v[12:13], v[10:11]
	v_mov_b64_e32 v[10:11], v[8:9]
	v_mov_b64_e32 v[8:9], v[6:7]
	v_mov_b64_e32 v[6:7], v[4:5]
	v_mov_b64_e32 v[4:5], v[2:3]
	v_mov_b64_e32 v[2:3], v[0:1]
	v_mov_b32_e32 v150, 0
	v_mov_b32_e32 v151, 0
	v_mov_b32_e32 v152, 0
	v_mov_b32_e32 v153, 0
	v_mov_b32_e32 v154, 0
	v_mov_b32_e32 v155, 0
	v_mov_b32_e32 v156, 0
	v_mov_b32_e32 v157, 0
	v_mov_b32_e32 v158, 0
	v_mov_b32_e32 v159, 0
	v_mov_b32_e32 v160, 0
	v_mov_b32_e32 v161, 0
	v_mov_b32_e32 v162, 0
	v_mov_b32_e32 v163, 0
	v_mov_b32_e32 v164, 0
	v_mov_b32_e32 v165, 0
	s_barrier
	s_waitcnt vmcnt(0)
	ds_write_b128 v127, v[106:109]
	ds_write_b128 v128, v[98:101]
	ds_write_b128 v129, v[102:105]
	ds_write2_b64 v130, v[90:91], v[92:93] offset1:1
	ds_write2_b64 v131, v[94:95], v[96:97] offset1:1
	s_cmp_ge_u32 1, s75
	s_cbranch_scc1 .Lmla_pre
	global_load_dwordx4 v[106:109], v118, s[18:19]
	global_load_dwordx4 v[98:101], v116, s[18:19]
	global_load_dwordx4 v[102:105], v114, s[18:19]
	global_load_dwordx4 v[90:93], v110, s[18:19]
	global_load_dwordx4 v[94:97], v112, s[18:19]
	v_add_u32_e32 v110, s8, v110
	v_add_u32_e32 v112, s8, v112
	v_add_u32_e32 v114, s10, v114
	v_add_u32_e32 v116, s10, v116
	v_add_u32_e32 v118, s10, v118
.Lmla_pre:
	s_waitcnt lgkmcnt(0)
	s_barrier
.LBB1_318:
	s_add_i32 s12, s21, 1
	s_cmp_ge_u32 s12, s75
	s_cbranch_scc1 .Lmla_c_a
	s_waitcnt vmcnt(0)
	v_add_u32_e32 v130, 0x8c00, v130
	v_add_u32_e32 v131, 0x8c00, v131
	ds_write_b128 v127, v[106:109] offset:35840
	ds_write_b128 v128, v[98:101] offset:35840
	ds_write_b128 v129, v[102:105] offset:35840
	ds_write2_b64 v130, v[90:91], v[92:93] offset1:1
	ds_write2_b64 v131, v[94:95], v[96:97] offset1:1
	s_add_i32 s12, s21, 2
	s_cmp_ge_u32 s12, s75
	s_cbranch_scc1 .Lmla_c_a
	global_load_dwordx4 v[106:109], v118, s[18:19]
	global_load_dwordx4 v[98:101], v116, s[18:19]
	global_load_dwordx4 v[102:105], v114, s[18:19]
	global_load_dwordx4 v[90:93], v110, s[18:19]
	global_load_dwordx4 v[94:97], v112, s[18:19]
	v_add_u32_e32 v110, s8, v110
	v_add_u32_e32 v112, s8, v112
	v_add_u32_e32 v114, s10, v114
	v_add_u32_e32 v116, s10, v116
	v_add_u32_e32 v118, s10, v118

; template <int DQK, int DV, bool BAND> ...
;     ...
;   for (int kt = kt_lo; kt < kt_hi; ++kt) {
;     __syncthreads();
;     if (!PREF) ALOAD(kt);
; #pragma unroll
;     for (int i = 0; i < KCH; ++i) { const int cid = tid + 256 * i, row = cid / KCPR, c8 = cid - row * KCPR; *(u32x4*)&Ks[row * KLD + c8 * 8] = kreg[i]; }
; #pragma unroll
;     for (int i = 0; i < VCH; ++i) { const int cid = tid + 256 * i, row = cid >> 3, c8 = cid & 7;
;       *(u32x2*)&Vs[row * VLD + c8 * 8] = u32x2{vreg[i][0], vreg[i][1]}; *(u32x2*)&Vs[row * VLD + c8 * 8 + 4] = u32x2{vreg[i][2], vreg[i][3]}; }
;     __syncthreads();
;     if (PREF && kt + 1 < kt_hi) ALOAD(kt + 1);
;     ...
;       const float m_ref = (m_run == -INFINITY) ? 0.f : m_run;
;       float rs0 = 0.f, rs1 = 0.f;
; #pragma unroll
;       for (int r = 0; r < 16; ++r) { const float e0 = __builtin_amdgcn_exp2f(p0[r] - m_ref), e1 = __builtin_amdgcn_exp2f(p1[r] - m_ref); p0[r] = e0; p1[r] = e1; rs0 += e0; rs1 += e1; }
;       l_run += xhalf_sum(rs0 + rs1);
;       __builtin_amdgcn_s_setprio(1);
; #pragma unroll
;       for (int s = 0; s < 2; ++s) {
;         const u32x4 pu0 = {pk2(p0[8 * s], p0[8 * s + 1]), pk2(p0[8 * s + 2], p0[8 * s + 3]), pk2(p0[8 * s + 4], p0[8 * s + 5]), pk2(p0[8 * s + 6], p0[8 * s + 7])};
;         const u32x4 pu1 = {pk2(p1[8 * s], p1[8 * s + 1]), pk2(p1[8 * s + 2], p1[8 * s + 3]), pk2(p1[8 * s + 4], p1[8 * s + 5]), pk2(p1[8 * s + 6], p1[8 * s + 7])};
; #pragma unroll
;         for (int cb = 0; cb < NCB; ++cb) {
;           const u32x2 lo0 = *(const u32x2*)&Vs[(cb * 32 + r32) * VLD + 16 * s + 4 * hi];
;           const u32x2 hi0 = *(const u32x2*)&Vs[(cb * 32 + r32) * VLD + 16 * s + 4 * hi + 8];
;           const u32x4 v0 = {lo0[0], lo0[1], hi0[0], hi0[1]};
;           o[cb] = MFMA(__builtin_bit_cast(bf16x8, pu0), __builtin_bit_cast(bf16x8, v0), o[cb]);
;         }
; #pragma unroll
;         for (int cb = 0; cb < NCB; ++cb) {
;           const u32x2 lo1 = *(const u32x2*)&Vs[(cb * 32 + r32) * VLD + 32 + 16 * s + 4 * hi];
;           const u32x2 hi1 = *(const u32x2*)&Vs[(cb * 32 + r32) * VLD + 32 + 16 * s + 4 * hi + 8];
;           const u32x4 v1 = {lo1[0], lo1[1], hi1[0], hi1[1]};
;           o[cb] = MFMA(__builtin_bit_cast(bf16x8, pu1), __builtin_bit_cast(bf16x8, v1), o[cb]);
;         }
;       }
;       __builtin_amdgcn_s_setprio(0);
.Lmla_ex_a:
	v_exp_f32_e32 v34, v34
	v_exp_f32_e32 v35, v35
	v_exp_f32_e32 v36, v36
	v_exp_f32_e32 v37, v37
	v_exp_f32_e32 v38, v38
	v_exp_f32_e32 v39, v39
	v_exp_f32_e32 v40, v40
	v_exp_f32_e32 v41, v41
	v_exp_f32_e32 v42, v42
	v_exp_f32_e32 v43, v43
	v_exp_f32_e32 v44, v44
	v_exp_f32_e32 v45, v45
	v_exp_f32_e32 v46, v46
	v_exp_f32_e32 v47, v47
	v_exp_f32_e32 v48, v48
	v_exp_f32_e32 v49, v49
	v_exp_f32_e32 v50, v50
	v_exp_f32_e32 v51, v51
	v_exp_f32_e32 v52, v52
	v_exp_f32_e32 v53, v53
	v_exp_f32_e32 v54, v54
	v_exp_f32_e32 v55, v55
	v_exp_f32_e32 v56, v56
	v_exp_f32_e32 v57, v57
	v_exp_f32_e32 v58, v58
	v_exp_f32_e32 v59, v59
	v_exp_f32_e32 v60, v60
	v_exp_f32_e32 v61, v61
	v_exp_f32_e32 v62, v62
	v_exp_f32_e32 v63, v63
	v_exp_f32_e32 v64, v64
	v_exp_f32_e32 v65, v65
	s_nop 0
	v_pk_add_f32 v[168:169], v[34:35], v[36:37]
	v_pk_add_f32 v[170:171], v[38:39], v[40:41]
	v_pk_add_f32 v[168:169], v[42:43], v[168:169]
	v_pk_add_f32 v[170:171], v[44:45], v[170:171]
	v_pk_add_f32 v[168:169], v[46:47], v[168:169]
	v_pk_add_f32 v[170:171], v[48:49], v[170:171]
	v_pk_add_f32 v[168:169], v[50:51], v[168:169]
	v_pk_add_f32 v[170:171], v[52:53], v[170:171]
	v_pk_add_f32 v[168:169], v[54:55], v[168:169]
	v_pk_add_f32 v[170:171], v[56:57], v[170:171]
	v_pk_add_f32 v[168:169], v[58:59], v[168:169]
	v_pk_add_f32 v[170:171], v[60:61], v[170:171]
	v_pk_add_f32 v[168:169], v[62:63], v[168:169]
	v_pk_add_f32 v[170:171], v[64:65], v[170:171]
	v_pk_add_f32 v[168:169], v[168:169], v[170:171]
	s_nop 0
	v_add_f32_e32 v168, v168, v169
	v_mov_b32_e32 v169, v168
	s_nop 1
	v_permlane32_swap_b32_e32 v168, v169
	v_add_f32_e32 v168, v168, v169
	v_add_f32_e32 v126, v126, v168
	v_cvt_pk_bf16_f32 v34, v34, v35
	v_cvt_pk_bf16_f32 v35, v36, v37
	v_cvt_pk_bf16_f32 v36, v38, v39
	v_cvt_pk_bf16_f32 v37, v40, v41
	v_cvt_pk_bf16_f32 v38, v42, v43
	v_cvt_pk_bf16_f32 v39, v44, v45
	v_cvt_pk_bf16_f32 v40, v46, v47
	v_cvt_pk_bf16_f32 v41, v48, v49
	v_cvt_pk_bf16_f32 v50, v50, v51
	v_cvt_pk_bf16_f32 v51, v52, v53
	v_cvt_pk_bf16_f32 v52, v54, v55
	v_cvt_pk_bf16_f32 v53, v56, v57
	v_cvt_pk_bf16_f32 v54, v58, v59
	v_cvt_pk_bf16_f32 v55, v60, v61
	v_cvt_pk_bf16_f32 v56, v62, v63
	v_cvt_pk_bf16_f32 v57, v64, v65
	s_setprio 1
	s_waitcnt lgkmcnt(0)
	v_mfma_f32_32x32x16_bf16 v[2:17], v[34:37], v[208:211], v[2:17]
	v_mfma_f32_32x32x16_bf16 v[18:33], v[34:37], v[212:215], v[18:33]
	v_mfma_f32_32x32x16_bf16 v[2:17], v[50:53], v[216:219], v[2:17]
	v_mfma_f32_32x32x16_bf16 v[18:33], v[50:53], v[220:223], v[18:33]
	v_mfma_f32_32x32x16_bf16 v[2:17], v[38:41], v[224:227], v[2:17]
	v_mfma_f32_32x32x16_bf16 v[18:33], v[38:41], v[228:231], v[18:33]
	v_mfma_f32_32x32x16_bf16 v[2:17], v[54:57], v[232:235], v[2:17]
	v_mfma_f32_32x32x16_bf16 v[18:33], v[54:57], v[236:239], v[18:33]
	s_setprio 0
	v_mov_b32_e32 v133, v0
	s_add_i32 s21, s21, 1
	s_waitcnt lgkmcnt(0)
	s_barrier
	s_cmp_eq_u32 s75, s21
	s_cbranch_scc1 .LBB1_327
	s_add_i32 s12, s21, 1
	s_cmp_ge_u32 s12, s75
	s_cbranch_scc1 .Lmla_c_b
	s_waitcnt vmcnt(0)
	v_subrev_u32_e32 v130, 0x8c00, v130
	v_subrev_u32_e32 v131, 0x8c00, v131
	ds_write_b128 v127, v[106:109]
	ds_write_b128 v128, v[98:101]
	ds_write_b128 v129, v[102:105]
	ds_write2_b64 v130, v[90:91], v[92:93] offset1:1
	ds_write2_b64 v131, v[94:95], v[96:97] offset1:1
	s_add_i32 s12, s21, 2
	s_cmp_ge_u32 s12, s75
	s_cbranch_scc1 .Lmla_c_b
	global_load_dwordx4 v[106:109], v118, s[18:19]
	global_load_dwordx4 v[98:101], v116, s[18:19]
	global_load_dwordx4 v[102:105], v114, s[18:19]
	global_load_dwordx4 v[90:93], v110, s[18:19]
	global_load_dwordx4 v[94:97], v112, s[18:19]
	v_add_u32_e32 v110, s8, v110
	v_add_u32_e32 v112, s8, v112
	v_add_u32_e32 v114, s10, v114
	v_add_u32_e32 v116, s10, v116
	v_add_u32_e32 v118, s10, v118
; #define MFMA(a, b, c) __builtin_amdgcn_mfma_f32_32x32x16_bf16((a), (b), (c), 0, 0, 0)
; DI float xhalf_max(float x) { const auto rr = __builtin_amdgcn_permlane32_swap(__float_as_uint(x), __float_as_uint(x), false, false); return fmaxf(__uint_as_float(rr[0]), __uint_as_float(rr[1])); }
; template <int DQK, int DV, bool BAND> ...
;     ...
;     if constexpr (DQK < 128) {
;       f32x16 p0, p1;
; #pragma unroll
;       for (int r = 0; r < 16; ++r) { p0[r] = 0.f; p1[r] = 0.f; }
;       __builtin_amdgcn_s_setprio(1);
; #pragma unroll
;       for (int d0 = 0; d0 < ND0; ++d0) {
;         const bf16x8 k0f = *(const bf16x8*)&Ks[r32 * KLD + d0 * 16 + hi * 8];
;         const bf16x8 k1f = *(const bf16x8*)&Ks[(32 + r32) * KLD + d0 * 16 + hi * 8];
;         p0 = MFMA(k0f, qf[d0], p0); p1 = MFMA(k1f, qf[d0], p1);
;       }
;       __builtin_amdgcn_s_setprio(0);
;       float mx = fmaxf(p0[0], p1[0]);
; #pragma unroll
;       for (int r = 1; r < 16; ++r) mx = fmaxf(mx, fmaxf(p0[r], p1[r]));
;       mx = xhalf_max(mx);
;       if (__builtin_amdgcn_ballot_w64(mx > m_run + 8.f) != 0ull) {
;         const float m_new = fmaxf(m_run, mx); const float m_use = (m_new == -INFINITY) ? 0.f : m_new;
;         const float alpha = __builtin_amdgcn_exp2f(m_run - m_use);
;         l_run *= alpha; m_run = m_new;
;         if (hi == 0) sc[r32] = alpha;
;         __builtin_amdgcn_fence(__ATOMIC_RELEASE, "wavefront");
;         __builtin_amdgcn_wave_barrier();
; #pragma unroll
;         for (int g4 = 0; g4 < 4; ++g4) { const f32x4 a4 = *(const f32x4*)&sc[8 * g4 + 4 * hi];
; #pragma unroll
;           for (int cb = 0; cb < NCB; ++cb)
; #pragma unroll
;             for (int j = 0; j < 4; ++j) o[cb][4 * g4 + j] *= a4[j]; }
;         __builtin_amdgcn_wave_barrier();
;       }
;       const float m_ref = (m_run == -INFINITY) ? 0.f : m_run;
.Lmla_c_b:
	s_setprio 1
	ds_read_b128 v[208:211], v132 offset:35840
	ds_read_b128 v[212:215], v132 offset:42496
	ds_read_b128 v[216:219], v132 offset:35872
	ds_read_b128 v[220:223], v132 offset:42528
	ds_read_b128 v[224:227], v132 offset:35904
	ds_read_b128 v[228:231], v132 offset:42560
	ds_read_b128 v[232:235], v132 offset:35936
	ds_read_b128 v[236:239], v132 offset:42592
	ds_read_b128 v[240:243], v132 offset:35968
	ds_read_b128 v[244:247], v132 offset:42624
	ds_read_b128 v[248:251], v132 offset:36000
	ds_read_b128 v[134:137], v132 offset:42656
	v_add_u32_e32 v166, 0xcc00, v125
	v_add_u32_e32 v167, 0xdc00, v125
	s_waitcnt lgkmcnt(11)
	v_mfma_f32_32x32x16_bf16 v[34:49], v[208:211], v[66:69], v[150:165]
	s_waitcnt lgkmcnt(10)
	v_mfma_f32_32x32x16_bf16 v[50:65], v[212:215], v[66:69], v[150:165]
	s_waitcnt lgkmcnt(9)
	v_mfma_f32_32x32x16_bf16 v[34:49], v[216:219], v[70:73], v[34:49]
	s_waitcnt lgkmcnt(8)
	v_mfma_f32_32x32x16_bf16 v[50:65], v[220:223], v[70:73], v[50:65]
	s_waitcnt lgkmcnt(7)
	v_mfma_f32_32x32x16_bf16 v[34:49], v[224:227], v[74:77], v[34:49]
	s_waitcnt lgkmcnt(6)
	v_mfma_f32_32x32x16_bf16 v[50:65], v[228:231], v[74:77], v[50:65]
	s_waitcnt lgkmcnt(5)
	v_mfma_f32_32x32x16_bf16 v[34:49], v[232:235], v[78:81], v[34:49]
	s_waitcnt lgkmcnt(4)
	v_mfma_f32_32x32x16_bf16 v[50:65], v[236:239], v[78:81], v[50:65]
	s_waitcnt lgkmcnt(3)
	v_mfma_f32_32x32x16_bf16 v[34:49], v[240:243], v[82:85], v[34:49]
	s_waitcnt lgkmcnt(2)
	v_mfma_f32_32x32x16_bf16 v[50:65], v[244:247], v[82:85], v[50:65]
	s_waitcnt lgkmcnt(1)
	v_mfma_f32_32x32x16_bf16 v[34:49], v[248:251], v[86:89], v[34:49]
	s_waitcnt lgkmcnt(0)
	v_mfma_f32_32x32x16_bf16 v[50:65], v[134:137], v[86:89], v[50:65]
	s_setprio 0
	ds_read2_b64 v[208:211], v166 offset0:128 offset1:130
	ds_read2_b64 v[212:215], v167 offset0:160 offset1:162
	ds_read2_b64 v[216:219], v166 offset0:136 offset1:138
	ds_read2_b64 v[220:223], v167 offset0:168 offset1:170
	ds_read2_b64 v[224:227], v166 offset0:132 offset1:134
	ds_read2_b64 v[228:231], v167 offset0:164 offset1:166
	ds_read2_b64 v[232:235], v166 offset0:140 offset1:142
	ds_read2_b64 v[236:239], v167 offset0:172 offset1:174
	s_nop 10
	v_max3_f32 v0, v34, v50, v35
	v_max3_f32 v134, v51, v36, v52
	v_max3_f32 v0, v0, v37, v53
	v_max3_f32 v134, v134, v38, v54
	v_max3_f32 v0, v0, v39, v55
	v_max3_f32 v134, v134, v40, v56
	v_max3_f32 v0, v0, v41, v57
	v_max3_f32 v134, v134, v42, v58
	v_max3_f32 v0, v0, v43, v59
	v_max3_f32 v134, v134, v44, v60
	v_max3_f32 v0, v0, v45, v61
	v_max3_f32 v134, v134, v46, v62
	v_max3_f32 v0, v0, v47, v63
	v_max3_f32 v134, v134, v48, v64
	v_max3_f32 v0, v0, v49, v65
	v_max_f32_e32 v0, v0, v134
	v_mov_b32_e32 v134, v0
	s_nop 1
	v_permlane32_swap_b32_e32 v0, v134
	v_max_f32_e32 v0, v0, v134
	v_sub_f32_e32 v0, v0, v150
	v_add_f32_e32 v134, 0x41000000, v133
	v_cmp_gt_f32_e32 vcc, v0, v134
	s_cbranch_vccz .Lmla_nr_b
	v_max_f32_e32 v0, v0, v0
	v_max_f32_e32 v134, v133, v133
	v_max_f32_e32 v0, v134, v0
	v_cmp_neq_f32_e32 vcc, s7, v0
	s_nop 1
	v_cndmask_b32_e32 v134, 0, v0, vcc
	v_sub_f32_e32 v133, v133, v134
	v_exp_f32_e32 v133, v133
	v_add_f32_e32 v168, v150, v134
	s_and_saveexec_b64 s[22:23], s[36:37]
	ds_write_b32 v124, v133 offset:34816
	s_or_b64 exec, exec, s[22:23]
	s_waitcnt lgkmcnt(0)
	ds_read_b128 v[136:139], v120 offset:34816
	ds_read_b128 v[140:143], v120 offset:34848
	ds_read_b128 v[144:147], v120 offset:34880
	ds_read_b128 v[240:243], v120 offset:34912
	v_mul_f32_e32 v126, v126, v133
	v_sub_f32_e32 v34, v34, v168
	v_sub_f32_e32 v35, v35, v168
	v_sub_f32_e32 v36, v36, v168
	v_sub_f32_e32 v37, v37, v168
	v_sub_f32_e32 v38, v38, v168
	v_sub_f32_e32 v39, v39, v168
	v_sub_f32_e32 v40, v40, v168
	v_sub_f32_e32 v41, v41, v168
	v_sub_f32_e32 v42, v42, v168
	v_sub_f32_e32 v43, v43, v168
	v_sub_f32_e32 v44, v44, v168
	v_sub_f32_e32 v45, v45, v168
	v_sub_f32_e32 v46, v46, v168
	v_sub_f32_e32 v47, v47, v168
	v_sub_f32_e32 v48, v48, v168
	v_sub_f32_e32 v49, v49, v168
	v_sub_f32_e32 v50, v50, v168
	v_sub_f32_e32 v51, v51, v168
	v_sub_f32_e32 v52, v52, v168
	v_sub_f32_e32 v53, v53, v168
	v_sub_f32_e32 v54, v54, v168
	v_sub_f32_e32 v55, v55, v168
	v_sub_f32_e32 v56, v56, v168
	v_sub_f32_e32 v57, v57, v168
	v_sub_f32_e32 v58, v58, v168
	v_sub_f32_e32 v59, v59, v168
	v_sub_f32_e32 v60, v60, v168
	v_sub_f32_e32 v61, v61, v168
	v_sub_f32_e32 v62, v62, v168
	v_sub_f32_e32 v63, v63, v168
	v_sub_f32_e32 v64, v64, v168
	v_sub_f32_e32 v65, v65, v168
	v_sub_f32_e32 v150, 0, v134
	v_mov_b32_e32 v151, v150
	v_mov_b32_e32 v152, v150
	v_mov_b32_e32 v153, v150
	v_mov_b32_e32 v154, v150
	v_mov_b32_e32 v155, v150
	v_mov_b32_e32 v156, v150
	v_mov_b32_e32 v157, v150
	v_mov_b32_e32 v158, v150
	v_mov_b32_e32 v159, v150
	v_mov_b32_e32 v160, v150
	v_mov_b32_e32 v161, v150
	v_mov_b32_e32 v162, v150
	v_mov_b32_e32 v163, v150
	v_mov_b32_e32 v164, v150
	v_mov_b32_e32 v165, v150
	s_waitcnt lgkmcnt(0)
	v_pk_mul_f32 v[2:3], v[2:3], v[136:137]
	v_pk_mul_f32 v[4:5], v[4:5], v[138:139]
	v_pk_mul_f32 v[6:7], v[6:7], v[140:141]
	v_pk_mul_f32 v[8:9], v[8:9], v[142:143]
	v_pk_mul_f32 v[10:11], v[10:11], v[144:145]
	v_pk_mul_f32 v[12:13], v[12:13], v[146:147]
	v_pk_mul_f32 v[14:15], v[14:15], v[240:241]
	v_pk_mul_f32 v[16:17], v[16:17], v[242:243]
	v_pk_mul_f32 v[18:19], v[18:19], v[136:137]
	v_pk_mul_f32 v[20:21], v[20:21], v[138:139]
	v_pk_mul_f32 v[22:23], v[22:23], v[140:141]
	v_pk_mul_f32 v[24:25], v[24:25], v[142:143]
	v_pk_mul_f32 v[26:27], v[26:27], v[144:145]
	v_pk_mul_f32 v[28:29], v[28:29], v[146:147]
	v_pk_mul_f32 v[30:31], v[30:31], v[240:241]
	v_pk_mul_f32 v[32:33], v[32:33], v[242:243]
	s_branch .Lmla_ex_b

; #define MFMA(a, b, c) __builtin_amdgcn_mfma_f32_32x32x16_bf16((a), (b), (c), 0, 0, 0)
; DI unsigned pk2(float a, float b) { f2_t v = {a, b}; bf2_t r = __builtin_convertvector(v, bf2_t); return __builtin_bit_cast(unsigned, r); }
; DI float xhalf_sum(float x) { const auto rr = __builtin_amdgcn_permlane32_swap(__float_as_uint(x), __float_as_uint(x), false, false); return __uint_as_float(rr[0]) + __uint_as_float(rr[1]); }
; template <int DQK, int DV, bool BAND> ...
;     ...
;       const float m_ref = (m_run == -INFINITY) ? 0.f : m_run;
;       float rs0 = 0.f, rs1 = 0.f;
; #pragma unroll
;       for (int r = 0; r < 16; ++r) { const float e0 = __builtin_amdgcn_exp2f(p0[r] - m_ref), e1 = __builtin_amdgcn_exp2f(p1[r] - m_ref); p0[r] = e0; p1[r] = e1; rs0 += e0; rs1 += e1; }
;       l_run += xhalf_sum(rs0 + rs1);
;       __builtin_amdgcn_s_setprio(1);
; #pragma unroll
;       for (int s = 0; s < 2; ++s) {
;         const u32x4 pu0 = {pk2(p0[8 * s], p0[8 * s + 1]), pk2(p0[8 * s + 2], p0[8 * s + 3]), pk2(p0[8 * s + 4], p0[8 * s + 5]), pk2(p0[8 * s + 6], p0[8 * s + 7])};
;         const u32x4 pu1 = {pk2(p1[8 * s], p1[8 * s + 1]), pk2(p1[8 * s + 2], p1[8 * s + 3]), pk2(p1[8 * s + 4], p1[8 * s + 5]), pk2(p1[8 * s + 6], p1[8 * s + 7])};
; #pragma unroll
;         for (int cb = 0; cb < NCB; ++cb) {
;           const u32x2 lo0 = *(const u32x2*)&Vs[(cb * 32 + r32) * VLD + 16 * s + 4 * hi];
;           const u32x2 hi0 = *(const u32x2*)&Vs[(cb * 32 + r32) * VLD + 16 * s + 4 * hi + 8];
;           const u32x4 v0 = {lo0[0], lo0[1], hi0[0], hi0[1]};
;           o[cb] = MFMA(__builtin_bit_cast(bf16x8, pu0), __builtin_bit_cast(bf16x8, v0), o[cb]);
;         }
; #pragma unroll
;         for (int cb = 0; cb < NCB; ++cb) {
;           const u32x2 lo1 = *(const u32x2*)&Vs[(cb * 32 + r32) * VLD + 32 + 16 * s + 4 * hi];
;           const u32x2 hi1 = *(const u32x2*)&Vs[(cb * 32 + r32) * VLD + 32 + 16 * s + 4 * hi + 8];
;           const u32x4 v1 = {lo1[0], lo1[1], hi1[0], hi1[1]};
;           o[cb] = MFMA(__builtin_bit_cast(bf16x8, pu1), __builtin_bit_cast(bf16x8, v1), o[cb]);
;         }
;       }
;       __builtin_amdgcn_s_setprio(0);
.Lmla_ex_b:
	v_exp_f32_e32 v34, v34
	v_exp_f32_e32 v35, v35
	v_exp_f32_e32 v36, v36
	v_exp_f32_e32 v37, v37
	v_exp_f32_e32 v38, v38
	v_exp_f32_e32 v39, v39
	v_exp_f32_e32 v40, v40
	v_exp_f32_e32 v41, v41
	v_exp_f32_e32 v42, v42
	v_exp_f32_e32 v43, v43
	v_exp_f32_e32 v44, v44
	v_exp_f32_e32 v45, v45
	v_exp_f32_e32 v46, v46
	v_exp_f32_e32 v47, v47
	v_exp_f32_e32 v48, v48
	v_exp_f32_e32 v49, v49
	v_exp_f32_e32 v50, v50
	v_exp_f32_e32 v51, v51
	v_exp_f32_e32 v52, v52
	v_exp_f32_e32 v53, v53
	v_exp_f32_e32 v54, v54
	v_exp_f32_e32 v55, v55
	v_exp_f32_e32 v56, v56
	v_exp_f32_e32 v57, v57
	v_exp_f32_e32 v58, v58
	v_exp_f32_e32 v59, v59
	v_exp_f32_e32 v60, v60
	v_exp_f32_e32 v61, v61
	v_exp_f32_e32 v62, v62
	v_exp_f32_e32 v63, v63
	v_exp_f32_e32 v64, v64
	v_exp_f32_e32 v65, v65
	s_nop 0
	v_pk_add_f32 v[168:169], v[34:35], v[36:37]
	v_pk_add_f32 v[170:171], v[38:39], v[40:41]
	v_pk_add_f32 v[168:169], v[42:43], v[168:169]
	v_pk_add_f32 v[170:171], v[44:45], v[170:171]
	v_pk_add_f32 v[168:169], v[46:47], v[168:169]
	v_pk_add_f32 v[170:171], v[48:49], v[170:171]
	v_pk_add_f32 v[168:169], v[50:51], v[168:169]
	v_pk_add_f32 v[170:171], v[52:53], v[170:171]
	v_pk_add_f32 v[168:169], v[54:55], v[168:169]
	v_pk_add_f32 v[170:171], v[56:57], v[170:171]
	v_pk_add_f32 v[168:169], v[58:59], v[168:169]
	v_pk_add_f32 v[170:171], v[60:61], v[170:171]
	v_pk_add_f32 v[168:169], v[62:63], v[168:169]
	v_pk_add_f32 v[170:171], v[64:65], v[170:171]
	v_pk_add_f32 v[168:169], v[168:169], v[170:171]
	s_nop 0
	v_add_f32_e32 v168, v168, v169
	v_mov_b32_e32 v169, v168
	s_nop 1
	v_permlane32_swap_b32_e32 v168, v169
	v_add_f32_e32 v168, v168, v169
	v_add_f32_e32 v126, v126, v168
	v_cvt_pk_bf16_f32 v34, v34, v35
	v_cvt_pk_bf16_f32 v35, v36, v37
	v_cvt_pk_bf16_f32 v36, v38, v39
	v_cvt_pk_bf16_f32 v37, v40, v41
	v_cvt_pk_bf16_f32 v38, v42, v43
	v_cvt_pk_bf16_f32 v39, v44, v45
	v_cvt_pk_bf16_f32 v40, v46, v47
	v_cvt_pk_bf16_f32 v41, v48, v49
	v_cvt_pk_bf16_f32 v50, v50, v51
	v_cvt_pk_bf16_f32 v51, v52, v53
	v_cvt_pk_bf16_f32 v52, v54, v55
	v_cvt_pk_bf16_f32 v53, v56, v57
	v_cvt_pk_bf16_f32 v54, v58, v59
	v_cvt_pk_bf16_f32 v55, v60, v61
	v_cvt_pk_bf16_f32 v56, v62, v63
	v_cvt_pk_bf16_f32 v57, v64, v65
	s_setprio 1
	s_waitcnt lgkmcnt(0)
	v_mfma_f32_32x32x16_bf16 v[2:17], v[34:37], v[208:211], v[2:17]
	v_mfma_f32_32x32x16_bf16 v[18:33], v[34:37], v[212:215], v[18:33]
	v_mfma_f32_32x32x16_bf16 v[2:17], v[50:53], v[216:219], v[2:17]
	v_mfma_f32_32x32x16_bf16 v[18:33], v[50:53], v[220:223], v[18:33]
	v_mfma_f32_32x32x16_bf16 v[2:17], v[38:41], v[224:227], v[2:17]
	v_mfma_f32_32x32x16_bf16 v[18:33], v[38:41], v[228:231], v[18:33]
	v_mfma_f32_32x32x16_bf16 v[2:17], v[54:57], v[232:235], v[2:17]
	v_mfma_f32_32x32x16_bf16 v[18:33], v[54:57], v[236:239], v[18:33]
	s_setprio 0
	v_mov_b32_e32 v133, v0
	s_add_i32 s21, s21, 1
	s_waitcnt lgkmcnt(0)
	s_barrier
	s_cmp_eq_u32 s75, s21
	s_cbranch_scc1 .LBB1_327
	s_branch .LBB1_318
